# grid-barrier polling loops: back-off s_sleep 1 -> s_sleep 8 (121 sites)
# speedup vs baseline: 1.0067x; 1.0011x over previous
.LBB0_102:
	s_sleep 8
	global_load_dword v2, v0, s[2:3] offset:32 sc1
	s_waitcnt vmcnt(0)
	v_and_b32_e32 v2, 0xffff0000, v2
	v_cmp_ne_u32_e32 vcc, v2, v1
	s_or_b64 s[6:7], vcc, s[6:7]
	s_andn2_b64 exec, exec, s[6:7]
	s_cbranch_execnz .LBB0_102

.LBB0_110:
	global_load_dword v16, v15, s[50:51] offset:256 sc1
	global_load_dword v14, v15, s[50:51] offset:512 sc1
	global_load_dword v13, v15, s[50:51] offset:768 sc1
	global_load_dword v12, v15, s[50:51] offset:1024 sc1
	global_load_dword v11, v15, s[50:51] offset:1280 sc1
	global_load_dword v10, v15, s[50:51] offset:1536 sc1
	global_load_dword v9, v15, s[50:51] offset:1792 sc1
	global_load_dword v8, v15, s[50:51] offset:2048 sc1
	global_load_dword v7, v15, s[50:51] offset:2304 sc1
	global_load_dword v6, v15, s[50:51] offset:2560 sc1
	global_load_dword v5, v15, s[50:51] offset:2816 sc1
	global_load_dword v4, v15, s[50:51] offset:3072 sc1
	global_load_dword v3, v15, s[50:51] offset:3328 sc1
	global_load_dword v2, v15, s[50:51] offset:3584 sc1
	global_load_dword v1, v15, s[50:51] offset:3840 sc1
	global_load_dword v0, v15, s[6:7] sc1
	s_load_dword s8, s[0:1], 0x170
	s_waitcnt vmcnt(14)
	v_add_u32_e32 v17, v14, v16
	s_waitcnt vmcnt(13)
	v_add_u32_e32 v17, v17, v13
	s_waitcnt vmcnt(12)
	v_add_u32_e32 v17, v17, v12
	s_waitcnt vmcnt(11)
	v_add_u32_e32 v17, v17, v11
	s_waitcnt vmcnt(10)
	v_add_u32_e32 v17, v17, v10
	s_waitcnt vmcnt(9)
	v_add_u32_e32 v17, v17, v9
	s_waitcnt vmcnt(8)
	v_add_u32_e32 v17, v17, v8
	s_waitcnt vmcnt(7)
	v_add_u32_e32 v17, v17, v7
	s_waitcnt vmcnt(6)
	v_add_u32_e32 v17, v17, v6
	s_waitcnt vmcnt(5)
	v_add_u32_e32 v17, v17, v5
	s_waitcnt vmcnt(4)
	v_add_u32_e32 v17, v17, v4
	s_waitcnt vmcnt(3)
	v_add_u32_e32 v17, v17, v3
	s_waitcnt vmcnt(2)
	v_add_u32_e32 v17, v17, v2
	s_waitcnt vmcnt(1)
	v_add_u32_e32 v17, v17, v1
	s_waitcnt vmcnt(0)
	v_add_u32_e32 v17, v17, v0
	s_waitcnt lgkmcnt(0)
	v_cmp_eq_u32_e32 vcc, s8, v17
	s_mov_b64 s[8:9], -1
	s_cbranch_vccnz .LBB0_108
	s_cmp_lg_u32 s11, 0
	s_sleep 8
	s_cbranch_scc0 .LBB0_108
	global_load_dword v16, v15, s[50:51] offset:256 sc1
	global_load_dword v14, v15, s[50:51] offset:512 sc1
	global_load_dword v13, v15, s[50:51] offset:768 sc1
	global_load_dword v12, v15, s[50:51] offset:1024 sc1
	global_load_dword v11, v15, s[50:51] offset:1280 sc1
	global_load_dword v10, v15, s[50:51] offset:1536 sc1
	global_load_dword v9, v15, s[50:51] offset:1792 sc1
	global_load_dword v8, v15, s[50:51] offset:2048 sc1
	global_load_dword v7, v15, s[50:51] offset:2304 sc1
	global_load_dword v6, v15, s[50:51] offset:2560 sc1
	global_load_dword v5, v15, s[50:51] offset:2816 sc1
	global_load_dword v4, v15, s[50:51] offset:3072 sc1
	global_load_dword v3, v15, s[50:51] offset:3328 sc1
	global_load_dword v2, v15, s[50:51] offset:3584 sc1
	global_load_dword v1, v15, s[50:51] offset:3840 sc1
	global_load_dword v0, v15, s[6:7] sc1
	s_load_dword s8, s[0:1], 0x170
	s_waitcnt vmcnt(14)
	v_add_u32_e32 v17, v14, v16
	s_waitcnt vmcnt(13)
	v_add_u32_e32 v17, v17, v13
	s_waitcnt vmcnt(12)
	v_add_u32_e32 v17, v17, v12
	s_waitcnt vmcnt(11)
	v_add_u32_e32 v17, v17, v11
	s_waitcnt vmcnt(10)
	v_add_u32_e32 v17, v17, v10
	s_waitcnt vmcnt(9)
	v_add_u32_e32 v17, v17, v9
	s_waitcnt vmcnt(8)
	v_add_u32_e32 v17, v17, v8
	s_waitcnt vmcnt(7)
	v_add_u32_e32 v17, v17, v7
	s_waitcnt vmcnt(6)
	v_add_u32_e32 v17, v17, v6
	s_waitcnt vmcnt(5)
	v_add_u32_e32 v17, v17, v5
	s_waitcnt vmcnt(4)
	v_add_u32_e32 v17, v17, v4
	s_waitcnt vmcnt(3)
	v_add_u32_e32 v17, v17, v3
	s_waitcnt vmcnt(2)
	v_add_u32_e32 v17, v17, v2
	s_waitcnt vmcnt(1)
	v_add_u32_e32 v17, v17, v1
	s_waitcnt vmcnt(0)
	v_add_u32_e32 v17, v17, v0
	s_waitcnt lgkmcnt(0)
	v_cmp_ne_u32_e32 vcc, s8, v17
	s_mov_b64 s[8:9], -1
	s_cbranch_vccz .LBB0_109
	s_sleep 8
	s_add_i32 s11, s11, -2
	s_mov_b64 s[8:9], 0
	s_branch .LBB0_109

.LBB0_124:
	global_load_dword v2, v0, s[8:9] sc1
	s_or_b64 s[12:13], s[12:13], exec
	s_waitcnt vmcnt(0)
	v_cmp_eq_u32_e32 vcc, v2, v1
	s_and_saveexec_b64 s[14:15], vcc
	s_cbranch_execz .LBB0_123
	s_sleep 8
	global_load_dword v2, v0, s[8:9] sc1
	s_mov_b64 s[18:19], -1
	s_waitcnt vmcnt(0)
	v_cmp_eq_u32_e32 vcc, v2, v1
	s_and_saveexec_b64 s[16:17], vcc
	s_cbranch_execz .LBB0_122
	s_sleep 8
	global_load_dword v2, v0, s[8:9] sc1
	s_mov_b64 s[20:21], -1
	s_waitcnt vmcnt(0)
	v_cmp_eq_u32_e32 vcc, v2, v1
	s_and_saveexec_b64 s[18:19], vcc
	s_cbranch_execz .LBB0_121
	s_sleep 8
	global_load_dword v2, v0, s[8:9] sc1
	s_mov_b64 s[22:23], -1
	s_waitcnt vmcnt(0)
	v_cmp_eq_u32_e32 vcc, v2, v1
	s_and_saveexec_b64 s[20:21], vcc
	s_cbranch_execz .LBB0_120
	s_sleep 8
	global_load_dword v2, v0, s[8:9] sc1
	s_waitcnt vmcnt(0)
	v_cmp_eq_u32_e32 vcc, v2, v1
	s_and_saveexec_b64 s[24:25], vcc
	s_cbranch_execz .LBB0_119
	s_add_i32 s26, s26, -5
	s_cmp_eq_u32 s26, 0
	s_cselect_b64 s[22:23], -1, 0
	s_orn2_b64 s[22:23], s[22:23], exec
	s_sleep 8
	s_branch .LBB0_119

.LBB0_141:
	global_load_dword v2, v0, s[6:7] sc1
	s_or_b64 s[12:13], s[12:13], exec
	s_waitcnt vmcnt(0)
	v_cmp_eq_u32_e32 vcc, v2, v1
	s_and_saveexec_b64 s[14:15], vcc
	s_cbranch_execz .LBB0_140
	s_sleep 8
	global_load_dword v2, v0, s[6:7] sc1
	s_mov_b64 s[18:19], -1
	s_waitcnt vmcnt(0)
	v_cmp_eq_u32_e32 vcc, v2, v1
	s_and_saveexec_b64 s[16:17], vcc
	s_cbranch_execz .LBB0_139
	s_sleep 8
	global_load_dword v2, v0, s[6:7] sc1
	s_mov_b64 s[20:21], -1
	s_waitcnt vmcnt(0)
	v_cmp_eq_u32_e32 vcc, v2, v1
	s_and_saveexec_b64 s[18:19], vcc
	s_cbranch_execz .LBB0_138
	s_sleep 8
	global_load_dword v2, v0, s[6:7] sc1
	s_mov_b64 s[22:23], -1
	s_waitcnt vmcnt(0)
	v_cmp_eq_u32_e32 vcc, v2, v1
	s_and_saveexec_b64 s[20:21], vcc
	s_cbranch_execz .LBB0_137
	s_sleep 8
	global_load_dword v2, v0, s[6:7] sc1
	s_waitcnt vmcnt(0)
	v_cmp_eq_u32_e32 vcc, v2, v1
	s_and_saveexec_b64 s[24:25], vcc
	s_cbranch_execz .LBB0_136
	s_add_i32 s26, s26, -5
	s_cmp_eq_u32 s26, 0
	s_cselect_b64 s[22:23], -1, 0
	s_orn2_b64 s[22:23], s[22:23], exec
	s_sleep 8
	s_branch .LBB0_136

.LBB0_166:
	v_readlane_b32 s4, v254, 5
	global_load_dword v15, v177, s[50:51] offset:256 sc1
	global_load_dword v14, v177, s[50:51] offset:512 sc1
	global_load_dword v13, v177, s[50:51] offset:768 sc1
	global_load_dword v12, v177, s[50:51] offset:1024 sc1
	global_load_dword v11, v177, s[50:51] offset:1280 sc1
	global_load_dword v10, v177, s[50:51] offset:1536 sc1
	global_load_dword v9, v177, s[50:51] offset:1792 sc1
	global_load_dword v8, v177, s[50:51] offset:2048 sc1
	global_load_dword v7, v177, s[50:51] offset:2304 sc1
	global_load_dword v6, v177, s[50:51] offset:2560 sc1
	global_load_dword v5, v177, s[50:51] offset:2816 sc1
	global_load_dword v4, v177, s[50:51] offset:3072 sc1
	global_load_dword v2, v177, s[50:51] offset:3328 sc1
	global_load_dword v1, v177, s[50:51] offset:3584 sc1
	global_load_dword v0, v177, s[50:51] offset:3840 sc1
	v_readlane_b32 s5, v254, 6
	s_waitcnt vmcnt(13)
	v_add_u32_e32 v16, v14, v15
	s_nop 2
	global_load_dword v3, v177, s[4:5] sc1
	s_waitcnt vmcnt(13)
	v_add_u32_e32 v16, v16, v13
	s_waitcnt vmcnt(12)
	v_add_u32_e32 v16, v16, v12
	s_waitcnt vmcnt(11)
	v_add_u32_e32 v16, v16, v11
	s_waitcnt vmcnt(10)
	v_add_u32_e32 v16, v16, v10
	s_waitcnt vmcnt(9)
	v_add_u32_e32 v16, v16, v9
	s_waitcnt vmcnt(8)
	v_add_u32_e32 v16, v16, v8
	s_waitcnt vmcnt(7)
	v_add_u32_e32 v16, v16, v7
	s_waitcnt vmcnt(6)
	v_add_u32_e32 v16, v16, v6
	s_waitcnt vmcnt(5)
	v_add_u32_e32 v16, v16, v5
	s_waitcnt vmcnt(4)
	v_add_u32_e32 v16, v16, v4
	s_waitcnt vmcnt(3)
	v_add_u32_e32 v16, v16, v2
	s_waitcnt vmcnt(2)
	v_add_u32_e32 v16, v16, v1
	s_waitcnt vmcnt(1)
	v_add_u32_e32 v16, v16, v0
	v_readlane_b32 s4, v253, 1
	s_waitcnt vmcnt(0)
	v_add_u32_e32 v16, v16, v3
	v_cmp_eq_u32_e32 vcc, s4, v16
	s_mov_b64 s[4:5], -1
	s_cbranch_vccnz .LBB0_164
	s_cmp_lg_u32 s7, 0
	s_sleep 8
	s_cbranch_scc0 .LBB0_164
	v_readlane_b32 s4, v254, 5
	global_load_dword v15, v177, s[50:51] offset:256 sc1
	global_load_dword v14, v177, s[50:51] offset:512 sc1
	global_load_dword v13, v177, s[50:51] offset:768 sc1
	global_load_dword v12, v177, s[50:51] offset:1024 sc1
	global_load_dword v11, v177, s[50:51] offset:1280 sc1
	global_load_dword v10, v177, s[50:51] offset:1536 sc1
	global_load_dword v9, v177, s[50:51] offset:1792 sc1
	global_load_dword v8, v177, s[50:51] offset:2048 sc1
	global_load_dword v7, v177, s[50:51] offset:2304 sc1
	global_load_dword v6, v177, s[50:51] offset:2560 sc1
	global_load_dword v5, v177, s[50:51] offset:2816 sc1
	global_load_dword v4, v177, s[50:51] offset:3072 sc1
	global_load_dword v2, v177, s[50:51] offset:3328 sc1
	global_load_dword v1, v177, s[50:51] offset:3584 sc1
	global_load_dword v0, v177, s[50:51] offset:3840 sc1
	v_readlane_b32 s5, v254, 6
	s_waitcnt vmcnt(13)
	v_add_u32_e32 v16, v14, v15
	s_nop 2
	global_load_dword v3, v177, s[4:5] sc1
	s_waitcnt vmcnt(13)
	v_add_u32_e32 v16, v16, v13
	s_waitcnt vmcnt(12)
	v_add_u32_e32 v16, v16, v12
	s_waitcnt vmcnt(11)
	v_add_u32_e32 v16, v16, v11
	s_waitcnt vmcnt(10)
	v_add_u32_e32 v16, v16, v10
	s_waitcnt vmcnt(9)
	v_add_u32_e32 v16, v16, v9
	s_waitcnt vmcnt(8)
	v_add_u32_e32 v16, v16, v8
	s_waitcnt vmcnt(7)
	v_add_u32_e32 v16, v16, v7
	s_waitcnt vmcnt(6)
	v_add_u32_e32 v16, v16, v6
	s_waitcnt vmcnt(5)
	v_add_u32_e32 v16, v16, v5
	s_waitcnt vmcnt(4)
	v_add_u32_e32 v16, v16, v4
	s_waitcnt vmcnt(3)
	v_add_u32_e32 v16, v16, v2
	s_waitcnt vmcnt(2)
	v_add_u32_e32 v16, v16, v1
	s_waitcnt vmcnt(1)
	v_add_u32_e32 v16, v16, v0
	v_readlane_b32 s4, v253, 1
	s_waitcnt vmcnt(0)
	v_add_u32_e32 v16, v16, v3
	v_cmp_ne_u32_e32 vcc, s4, v16
	s_mov_b64 s[4:5], -1
	s_cbranch_vccz .LBB0_165
	s_sleep 8
	s_add_i32 s7, s7, -2
	s_mov_b64 s[4:5], 0
	s_branch .LBB0_165

.LBB0_180:
	global_load_dword v0, v177, s[6:7] sc1
	s_or_b64 s[10:11], s[10:11], exec
	s_waitcnt vmcnt(0)
	v_cmp_eq_u32_e32 vcc, v0, v1
	s_and_saveexec_b64 s[12:13], vcc
	s_cbranch_execz .LBB0_179
	s_sleep 8
	global_load_dword v0, v177, s[6:7] sc1
	s_mov_b64 s[16:17], -1
	s_waitcnt vmcnt(0)
	v_cmp_eq_u32_e32 vcc, v0, v1
	s_and_saveexec_b64 s[14:15], vcc
	s_cbranch_execz .LBB0_178
	s_sleep 8
	global_load_dword v0, v177, s[6:7] sc1
	s_mov_b64 s[18:19], -1
	s_waitcnt vmcnt(0)
	v_cmp_eq_u32_e32 vcc, v0, v1
	s_and_saveexec_b64 s[16:17], vcc
	s_cbranch_execz .LBB0_177
	s_sleep 8
	global_load_dword v0, v177, s[6:7] sc1
	s_mov_b64 s[20:21], -1
	s_waitcnt vmcnt(0)
	v_cmp_eq_u32_e32 vcc, v0, v1
	s_and_saveexec_b64 s[18:19], vcc
	s_cbranch_execz .LBB0_176
	s_sleep 8
	global_load_dword v0, v177, s[6:7] sc1
	s_waitcnt vmcnt(0)
	v_cmp_eq_u32_e32 vcc, v0, v1
	s_and_saveexec_b64 s[22:23], vcc
	s_cbranch_execz .LBB0_175
	s_add_i32 s24, s24, -5
	s_cmp_eq_u32 s24, 0
	s_cselect_b64 s[20:21], -1, 0
	s_orn2_b64 s[20:21], s[20:21], exec
	s_sleep 8
	s_branch .LBB0_175

.LBB0_197:
	v_readlane_b32 s10, v254, 9
	v_readlane_b32 s11, v254, 10
	s_or_b64 s[8:9], s[8:9], exec
	s_nop 3
	global_load_dword v0, v177, s[10:11] sc1
	s_waitcnt vmcnt(0)
	v_cmp_eq_u32_e32 vcc, v0, v1
	s_and_saveexec_b64 s[10:11], vcc
	s_cbranch_execz .LBB0_196
	v_readlane_b32 s12, v254, 9
	v_readlane_b32 s13, v254, 10
	s_sleep 8
	s_mov_b64 s[14:15], -1
	s_nop 2
	global_load_dword v0, v177, s[12:13] sc1
	s_waitcnt vmcnt(0)
	v_cmp_eq_u32_e32 vcc, v0, v1
	s_and_saveexec_b64 s[12:13], vcc
	s_cbranch_execz .LBB0_195
	v_readlane_b32 s14, v254, 9
	v_readlane_b32 s15, v254, 10
	s_sleep 8
	s_mov_b64 s[16:17], -1
	s_nop 2
	global_load_dword v0, v177, s[14:15] sc1
	s_waitcnt vmcnt(0)
	v_cmp_eq_u32_e32 vcc, v0, v1
	s_and_saveexec_b64 s[14:15], vcc
	s_cbranch_execz .LBB0_194
	v_readlane_b32 s16, v254, 9
	v_readlane_b32 s17, v254, 10
	s_sleep 8
	s_mov_b64 s[18:19], -1
	s_nop 2
	global_load_dword v0, v177, s[16:17] sc1
	s_waitcnt vmcnt(0)
	v_cmp_eq_u32_e32 vcc, v0, v1
	s_and_saveexec_b64 s[16:17], vcc
	s_cbranch_execz .LBB0_193
	v_readlane_b32 s18, v254, 9
	v_readlane_b32 s19, v254, 10
	s_sleep 8
	s_nop 3
	global_load_dword v0, v177, s[18:19] sc1
	s_mov_b64 s[18:19], -1
	s_waitcnt vmcnt(0)
	v_cmp_eq_u32_e32 vcc, v0, v1
	s_and_saveexec_b64 s[20:21], vcc
	s_cbranch_execz .LBB0_192
	s_add_i32 s22, s22, -5
	s_cmp_eq_u32 s22, 0
	s_cselect_b64 s[18:19], -1, 0
	s_orn2_b64 s[18:19], s[18:19], exec
	s_sleep 8
	s_branch .LBB0_192

.LBB0_890:
	global_load_dword v0, v177, s[6:7] sc1
	s_or_b64 s[10:11], s[10:11], exec
	s_waitcnt vmcnt(0)
	v_cmp_eq_u32_e32 vcc, v0, v1
	s_and_saveexec_b64 s[12:13], vcc
	s_cbranch_execz .LBB0_889
	s_sleep 8
	global_load_dword v0, v177, s[6:7] sc1
	s_mov_b64 s[16:17], -1
	s_waitcnt vmcnt(0)
	v_cmp_eq_u32_e32 vcc, v0, v1
	s_and_saveexec_b64 s[14:15], vcc
	s_cbranch_execz .LBB0_888
	s_sleep 8
	global_load_dword v0, v177, s[6:7] sc1
	s_mov_b64 s[18:19], -1
	s_waitcnt vmcnt(0)
	v_cmp_eq_u32_e32 vcc, v0, v1
	s_and_saveexec_b64 s[16:17], vcc
	s_cbranch_execz .LBB0_887
	s_sleep 8
	global_load_dword v0, v177, s[6:7] sc1
	s_mov_b64 s[20:21], -1
	s_waitcnt vmcnt(0)
	v_cmp_eq_u32_e32 vcc, v0, v1
	s_and_saveexec_b64 s[18:19], vcc
	s_cbranch_execz .LBB0_886
	s_sleep 8
	global_load_dword v0, v177, s[6:7] sc1
	s_waitcnt vmcnt(0)
	v_cmp_eq_u32_e32 vcc, v0, v1
	s_and_saveexec_b64 s[22:23], vcc
	s_cbranch_execz .LBB0_885
	s_add_i32 s25, s25, -5
	s_cmp_eq_u32 s25, 0
	s_cselect_b64 s[20:21], -1, 0
	s_orn2_b64 s[20:21], s[20:21], exec
	s_sleep 8
	s_branch .LBB0_885

.LBB0_945:
	global_load_dword v0, v177, s[6:7] sc1
	s_or_b64 s[10:11], s[10:11], exec
	s_waitcnt vmcnt(0)
	v_cmp_eq_u32_e32 vcc, v0, v1
	s_and_saveexec_b64 s[12:13], vcc
	s_cbranch_execz .LBB0_944
	s_sleep 8
	global_load_dword v0, v177, s[6:7] sc1
	s_mov_b64 s[16:17], -1
	s_waitcnt vmcnt(0)
	v_cmp_eq_u32_e32 vcc, v0, v1
	s_and_saveexec_b64 s[14:15], vcc
	s_cbranch_execz .LBB0_943
	s_sleep 8
	global_load_dword v0, v177, s[6:7] sc1
	s_mov_b64 s[18:19], -1
	s_waitcnt vmcnt(0)
	v_cmp_eq_u32_e32 vcc, v0, v1
	s_and_saveexec_b64 s[16:17], vcc
	s_cbranch_execz .LBB0_942
	s_sleep 8
	global_load_dword v0, v177, s[6:7] sc1
	s_mov_b64 s[20:21], -1
	s_waitcnt vmcnt(0)
	v_cmp_eq_u32_e32 vcc, v0, v1
	s_and_saveexec_b64 s[18:19], vcc
	s_cbranch_execz .LBB0_941
	s_sleep 8
	global_load_dword v0, v177, s[6:7] sc1
	s_waitcnt vmcnt(0)
	v_cmp_eq_u32_e32 vcc, v0, v1
	s_and_saveexec_b64 s[22:23], vcc
	s_cbranch_execz .LBB0_940
	s_add_i32 s27, s27, -5
	s_cmp_eq_u32 s27, 0
	s_cselect_b64 s[20:21], -1, 0
	s_orn2_b64 s[20:21], s[20:21], exec
	s_sleep 8
	s_branch .LBB0_940
